# kernel entry: the cooperative-groups grid sync is skipped (the first grid_barrier's census wait already covers late workgroups; LDS tables only need the workgroup barrier); XCC-class check read after
# speedup vs baseline: 1.0002x; 1.0002x over previous
.LBB0_5:
	s_or_b64 exec, exec, s[4:5]
	v_lshrrev_b32_e32 v2, 20, v0
	v_lshrrev_b32_e32 v0, 10, v0
	v_or_b32_e32 v0, v0, v2
	s_movk_i32 s0, 0x3ff
	v_and_or_b32 v0, v0, s0, v1
	v_cmp_eq_u32_e32 vcc, 0, v0
	s_waitcnt lgkmcnt(0)
	s_barrier
	s_and_saveexec_b64 s[4:5], vcc
	s_branch .LBB0_15
	buffer_wbl2 sc1
	s_waitcnt vmcnt(0)
	s_load_dwordx2 s[6:7], s[6:7], 0x58
	v_mov_b32_e32 v2, 0
	s_mov_b64 s[8:9], exec
	v_mbcnt_lo_u32_b32 v1, s8, 0
	v_mbcnt_hi_u32_b32 v1, s9, v1
	s_waitcnt lgkmcnt(0)
	global_load_dword v0, v2, s[6:7] offset:40
	v_cmp_eq_u32_e32 vcc, 0, v1
	s_and_saveexec_b64 s[10:11], vcc
	s_cbranch_execz .LBB0_8
	s_bcnt1_i32_b64 s0, s[8:9]
	v_mov_b32_e32 v3, s0
	global_atomic_add v3, v2, v3, s[6:7] offset:32 sc0

.LBB0_147:
	s_or_b64 exec, exec, s[4:5]
	s_cmpk_lt_i32 s71, 0x400
	s_cselect_b64 s[0:1], -1, 0
	s_ashr_i32 s2, s71, 7
	s_ashr_i32 s3, s2, 31
	s_lshl_b64 s[4:5], s[2:3], 12
	s_lshl_b32 s2, s71, 5
	s_and_b32 s2, s2, 0xfe0
	s_or_b32 s4, s4, s2
	s_lshl_b32 s2, s71, 9
	v_writelane_b32 v255, s4, 0
	v_cndmask_b32_e64 v0, 0, 1, s[0:1]
	s_add_i32 s0, 0, 0x20000
	v_writelane_b32 v255, s5, 1
	v_writelane_b32 v255, s2, 2
	s_add_i32 s2, s71, s72
	s_lshl_b32 s2, s2, 5
	v_writelane_b32 v255, s2, 3
	v_writelane_b32 v255, s0, 4
	s_add_i32 s0, 0, 0x6200
	v_writelane_b32 v255, s0, 5
	v_cmp_ne_u32_e64 s[0:1], 1, v0
	s_lshl_b32 s83, s72, 5
	s_add_i32 s86, 0, 0x23500
	v_writelane_b32 v255, s0, 6
	s_add_i32 s87, 0, 0x23504
	v_mov_b32_e32 v1, 0
	v_writelane_b32 v255, s1, 7
	v_writelane_b32 v255, s84, 8
	s_add_i32 s73, 0, 0x10200
	v_mov_b32_e32 v220, 0x358637bd
	v_writelane_b32 v255, s85, 9
	v_writelane_b32 v255, s71, 10
	v_writelane_b32 v255, s83, 11
	v_writelane_b32 v255, s86, 12
	s_mov_b32 s33, 0x800000
	s_movk_i32 s61, 0x500
	v_mov_b32_e32 v221, 0x1000
	v_mov_b32_e32 v254, 0x7000
	v_mov_b32_e32 v231, 0x2000
	s_movk_i32 s79, 0x280
	s_brev_b32 s88, 18
	s_mov_b32 s89, 0xfe5163ab
	s_mov_b32 s90, 0x3c439041
	s_mov_b32 s91, 0xdb629599
	s_mov_b32 s92, 0xf534ddc0
	s_mov_b32 s93, 0xfc2757d1
	s_mov_b32 s94, 0x4e441529
	s_mov_b32 s95, 0xa2f9836e
	s_mov_b32 s96, 0x3fc90fda
	s_mov_b32 s97, 0x3f22f983
	s_mov_b32 s80, 0xbfc90fda
	s_mov_b32 s82, 0xc2ce8ed0
	s_mov_b32 s81, 0x42b17218
	v_mov_b32_e32 v224, 0x3c0881c4
	v_mov_b32_e32 v225, 0xbab64f3b
	s_brev_b32 s75, 1
	s_movk_i32 s76, 0x1f8
	v_mov_b32_e32 v226, 1
	v_not_b32_e32 v227, 63
	v_not_b32_e32 v228, 31
	v_mov_b32_e32 v229, 0x7f800000
	v_mov_b32_e32 v230, 0x7fc00000
	v_mov_b64_e32 v[170:171], 0x67f
	v_mov_b32_e32 v234, 0x7f
	v_mov_b32_e32 v235, 0xff800000
	v_mov_b64_e32 v[172:173], 0x200
	v_mov_b64_e32 v[174:175], 0x1ff
	v_mov_b64_e32 v[176:177], 0xaff
	v_mov_b64_e32 v[178:179], 0xb00
	s_mov_b32 s48, 0xbfb8aa3b
	s_movk_i32 s77, 0xd1
	s_add_i32 s49, 0, 0x11000
	s_movk_i32 s62, 0x161
	s_movk_i32 s63, 0x1600
	s_mov_b32 s8, 0
	s_mov_b32 s51, 0
	s_mov_b64 s[54:55], 0x80
	s_mov_b64 s[0:1], 0x90
	s_mov_b64 s[66:67], 0xa0
	s_mov_b64 s[68:69], 0xb0
	s_mov_b32 s70, 0x3f317218
	s_mov_b32 s44, 0x3f803f80
	v_writelane_b32 v255, s87, 13
	s_waitcnt lgkmcnt(0)
	s_barrier
	s_load_dwordx2 s[100:101], s[84:85], 0x110
	v_mbcnt_lo_u32_b32 v10, -1, 0
	v_and_b32_e32 v10, 7, v10
	v_lshlrev_b32_e32 v10, 3, v10
	v_add_u32_e32 v10, 0x8000, v10
	s_waitcnt lgkmcnt(0)
	global_load_dwordx2 v[10:11], v10, s[100:101] sc1
	s_waitcnt vmcnt(0)
	v_add_u32_e32 v10, v10, v11
	v_cmp_ne_u32_e32 vcc, 17, v10
	s_nop 1
	s_cmp_eq_u64 vcc, 0
	s_cselect_b32 s100, 1, 0
	s_cselect_b32 s101, 1, 8
	s_nop 0
	v_writelane_b32 v255, s100, 40
	v_writelane_b32 v255, s101, 41
	s_branch .LBB0_149
